# MLA loop: one static s_setprio 1 for the younger half (waves 4-7) for the whole key loop, reset at loop exit
# baseline (speedup 1.0000x reference)
.LBB0_42:
	v_add_u32_e32 v166, 0x8000, v166
	v_add_u32_e32 v167, 0x8000, v168
	v_add_u32_e32 v168, 0x8000, v170
	v_add_u32_e32 v169, 0x8000, v172
	v_add_u32_e32 v170, 0x8000, v174
	v_add_u32_e32 v171, 0x8000, v176
	v_add_u32_e32 v172, 0x8000, v178
	v_add_u32_e32 v173, 0x8000, v180
	v_mov_b32_e32 v174, v183
	v_mov_b32_e32 v175, v193
	v_mov_b32_e32 v176, v195
	v_mov_b32_e32 v177, v197
	v_mov_b32_e32 v178, v140
	v_mov_b32_e32 v179, v142
	v_add_u32_e32 v180, 0x100, v138
	v_add_u32_e32 v181, 0x180, v138
	v_mov_b32_e32 v182, v136
	s_add_u32 s98, s74, 0x13480000
	s_addc_u32 s99, s75, 0
	s_add_u32 s100, s74, 0xae04000
	s_addc_u32 s101, s75, 0
	v_mov_b32_e32 v144, v158
	v_mov_b32_e32 v145, v159
	v_mov_b32_e32 v146, v156
	v_mov_b32_e32 v147, v157
	v_mov_b32_e32 v148, v154
	v_mov_b32_e32 v149, v155
	v_mov_b32_e32 v150, v152
	v_mov_b32_e32 v151, v153
	v_mov_b32_e32 v152, v134
	v_mov_b32_e32 v153, v135
	v_mov_b32_e32 v154, v132
	v_mov_b32_e32 v155, v133
	v_mov_b32_e32 v156, v130
	v_mov_b32_e32 v157, v131
	v_mov_b32_e32 v158, v128
	v_mov_b32_e32 v159, v129
	v_mov_b32_e32 v242, v198
	v_sub_f32_e32 v198, 0, v222
	v_sub_f32_e32 v199, 0, v222
	v_sub_f32_e32 v200, 0, v222
	v_sub_f32_e32 v201, 0, v222
	v_sub_f32_e32 v202, 0, v222
	v_sub_f32_e32 v203, 0, v222
	v_sub_f32_e32 v204, 0, v222
	v_sub_f32_e32 v205, 0, v222
	v_sub_f32_e32 v206, 0, v222
	v_sub_f32_e32 v207, 0, v222
	v_sub_f32_e32 v208, 0, v222
	v_sub_f32_e32 v209, 0, v222
	v_sub_f32_e32 v210, 0, v222
	v_sub_f32_e32 v211, 0, v222
	v_sub_f32_e32 v212, 0, v222
	v_sub_f32_e32 v213, 0, v222
	v_mov_b32_e32 v128, v236
	v_mov_b32_e32 v129, v238
	v_mov_b32_e32 v130, v234
	v_mov_b32_e32 v131, v237
	v_mov_b32_e32 v132, v233
	v_mov_b32_e32 v133, v235
	v_mov_b32_e32 v134, v231
	v_mov_b32_e32 v135, v232
	v_mov_b32_e32 v136, v228
	v_mov_b32_e32 v137, v230
	v_mov_b32_e32 v138, v227
	v_mov_b32_e32 v139, v229
	v_mov_b32_e32 v140, v224
	v_mov_b32_e32 v141, v226
	v_mov_b32_e32 v142, v223
	v_mov_b32_e32 v143, v225
	v_readfirstlane_b32 s8, v191
	s_nop 3
	s_lshr_b32 s8, s8, 6
	s_cmp_ge_u32 s8, 4
	s_cbranch_scc0 .Lmla_prio
	s_setprio 1
.Lmla_prio:
	ds_read_b128 v[246:249], v164
	ds_read_b128 v[250:253], v164 offset:1024
	ds_read_b128 v[186:189], v164 offset:2048
	ds_read_b128 v[238:241], v164 offset:3072
	s_waitcnt lgkmcnt(0)

.Lmla_nors_B:
	s_add_i32 s8, s14, 1
	s_cmp_lg_u32 s14, 2
	s_cselect_b32 s52, s8, 0
	s_add_i32 s8, s15, 1
	s_cmp_lg_u32 s15, 2
	s_cselect_b32 s49, s8, 0
	s_waitcnt vmcnt(0) lgkmcnt(0)
	s_barrier
	s_add_i32 s48, s48, 2
	s_cmp_lt_u32 s48, 61
	s_cbranch_scc1 .Lmla_loop
	v_mov_b32_e32 v236, v128
	v_mov_b32_e32 v238, v129
	v_mov_b32_e32 v234, v130
	v_mov_b32_e32 v237, v131
	v_mov_b32_e32 v233, v132
	v_mov_b32_e32 v235, v133
	v_mov_b32_e32 v231, v134
	v_mov_b32_e32 v232, v135
	v_mov_b32_e32 v228, v136
	v_mov_b32_e32 v230, v137
	v_mov_b32_e32 v227, v138
	v_mov_b32_e32 v229, v139
	v_mov_b32_e32 v224, v140
	v_mov_b32_e32 v226, v141
	v_mov_b32_e32 v223, v142
	v_mov_b32_e32 v225, v143
	v_mov_b32_e32 v134, v152
	v_mov_b32_e32 v135, v153
	v_mov_b32_e32 v132, v154
	v_mov_b32_e32 v133, v155
	v_mov_b32_e32 v130, v156
	v_mov_b32_e32 v131, v157
	v_mov_b32_e32 v128, v158
	v_mov_b32_e32 v129, v159
	v_mov_b32_e32 v158, v144
	v_mov_b32_e32 v159, v145
	v_mov_b32_e32 v156, v146
	v_mov_b32_e32 v157, v147
	v_mov_b32_e32 v154, v148
	v_mov_b32_e32 v155, v149
	v_mov_b32_e32 v152, v150
	v_mov_b32_e32 v153, v151
	s_setprio 0
	v_sub_f32_e32 v222, 0, v198
	v_mov_b32_e32 v144, v242
	v_mov_b32_e32 v198, v242
	v_add_u32_e32 v199, 0x8000, v166
	v_add_u32_e32 v200, 0x8000, v167
	v_add_u32_e32 v201, 0x8000, v168
	v_add_u32_e32 v202, 0x8000, v169
	v_add_u32_e32 v214, 0x8000, v170
	v_add_u32_e32 v215, 0x8000, v171
	v_add_u32_e32 v216, 0x8000, v172
	v_add_u32_e32 v217, 0x8000, v173
	v_add_u32_e32 v219, 0x2000, v174
	v_add_u32_e32 v218, 0x2000, v175
	v_add_u32_e32 v220, 0x2000, v176
	v_add_u32_e32 v221, 0x2000, v177
	v_mov_b32_e32 v203, v191
	v_mov_b32_e32 v204, 0x358637bd
	v_mov_b32_e32 v205, 0x260
	v_mov_b32_e32 v206, 1
	v_mov_b32_e32 v207, 0xf149f2ca
	v_mbcnt_lo_u32_b32 v208, -1, 0
	v_mbcnt_hi_u32_b32 v208, -1, v208
	v_mov_b32_e32 v209, 0x1450
	v_mov_b64_e32 v[210:211], 0x400
	v_mov_b32_e32 v212, 0x1c70
	v_and_b32_e32 v213, 63, v191
	v_mov_b32_e32 v242, 0
	v_mov_b32_e32 v243, 0
	v_mov_b32_e32 v244, 0
	v_mov_b32_e32 v245, 0
